# MIX-2 work queue order: independent conv items moved right behind the chain items (short dependent items last)
# speedup vs baseline: 1.0019x; 1.0019x over previous
.LBB0_533:
	s_or_b64 exec, exec, s[2:3]
	s_waitcnt lgkmcnt(0)
	s_barrier
	s_waitcnt vmcnt(0)
	ds_read_b32 v0, v201 offset:64512
	s_movk_i32 s2, 0x76b
	s_waitcnt lgkmcnt(0)
	v_cmp_lt_i32_e32 vcc, s2, v0
	v_readfirstlane_b32 s21, v0
	s_mov_b64 s[2:3], -1
	s_cbranch_vccnz .LBB0_528
	s_cmp_lt_u32 s21, 64
	s_cbranch_scc1 .Lmo_done
	s_cmp_lt_u32 s21, 0x2c8
	s_cbranch_scc0 .Lmo_b
	s_add_u32 s21, s21, 0x4a4
	s_branch .Lmo_done
.Lmo_b:
	s_sub_u32 s21, s21, 0x288
